# phase-0 in_w transpose: all 8 tiles' loads in flight up front, double-buffered LDS transpose with one barrier per tile
# speedup vs baseline: 1.0548x; 1.0037x over previous
; __device__ __forceinline__ unsigned cvt_pk_bf16(float lo, float hi) { unsigned r; asm volatile("v_cvt_pk_bf16_f32 %0, %1, %2" : "=v"(r) : "v"(lo), "v"(hi)); return r; }
; __device__ void phase0(const Params& p, LAS unsigned char* lds) {
;     ...
;     {
;         const int r0 = tid >> 4, c4 = (tid & 15) * 4;
;         int job = blockIdx.x;
;         f32x4 va, vb;
;         { const int kt = job & 15, ntile = job >> 4; const int n0 = ntile * 64, k0 = kt * 64; const int c0 = n0 < 5120 ? n0 : n0 + 16;
;           va = __builtin_nontemporal_load((const f32x4*)(p.in_w + (size_t)(k0 + r0) * 8208 + c0 + c4)); vb = __builtin_nontemporal_load((const f32x4*)(p.in_w + (size_t)(k0 + r0 + 32) * 8208 + c0 + c4)); }
;         for (; job < 2048; job += gridDim.x) {
;             const int kt = job & 15, ntile = job >> 4; const int n0 = ntile * 64, k0 = kt * 64;
;             T[r0 * 65 + c4] = va[0]; T[r0 * 65 + c4 + 1] = va[1]; T[r0 * 65 + c4 + 2] = va[2]; T[r0 * 65 + c4 + 3] = va[3];
;             T[(r0 + 32) * 65 + c4] = vb[0]; T[(r0 + 32) * 65 + c4 + 1] = vb[1]; T[(r0 + 32) * 65 + c4 + 2] = vb[2]; T[(r0 + 32) * 65 + c4 + 3] = vb[3];
;             __syncthreads();
;             const int nj = job + gridDim.x;
;             if (nj < 2048) { const int kt2 = nj & 15, nt2 = nj >> 4; const int n2 = nt2 * 64, k2 = kt2 * 64; const int c2 = n2 < 5120 ? n2 : n2 + 16;
;                 va = __builtin_nontemporal_load((const f32x4*)(p.in_w + (size_t)(k2 + r0) * 8208 + c2 + c4)); vb = __builtin_nontemporal_load((const f32x4*)(p.in_w + (size_t)(k2 + r0 + 32) * 8208 + c2 + c4)); }
;             { const int n = tid >> 3, kc = (tid & 7) * 8; float f[8];
; #pragma unroll
;               for (int j = 0; j < 8; ++j) f[j] = T[(kc + j) * 65 + n];
;               u32x4 w; w.x = cvt_pk_bf16(f[0], f[1]); w.y = cvt_pk_bf16(f[2], f[3]); w.z = cvt_pk_bf16(f[4], f[5]); w.w = cvt_pk_bf16(f[6], f[7]);
;               *(u32x4*)(WinT + (size_t)(n0 + n) * 1024 + k0 + kc) = w; }
;             __syncthreads();
;         }
.LBB0_70:
	s_or_b64 exec, exec, s[4:5]
	s_add_u32 s20, s70, 0x2400000
	s_addc_u32 s21, s71, 0
	v_ashrrev_i32_e32 v14, 4, v224
	s_lshl_b32 s4, s2, 6
	s_and_b32 s3, s4, 0x3c0
	v_add_u32_e32 v2, s3, v14
	s_mov_b32 s5, 0x8040
	v_mul_lo_u32 v0, v2, s5
	v_lshlrev_b32_e32 v20, 2, v224
	v_and_b32_e32 v20, 60, v20
	v_lshl_add_u32 v30, v20, 2, v0
	v_add_u32_e32 v31, 0x100800, v30
	s_lshr_b32 s5, s2, 4
	s_lshl_b32 s5, s5, 8
	s_add_u32 s6, s50, s5
	s_addc_u32 s7, s51, 0
	global_load_dwordx4 v[128:131], v30, s[6:7] nt
	global_load_dwordx4 v[132:135], v31, s[6:7] nt
	s_add_u32 s6, s6, 4096
	s_addc_u32 s7, s7, 0
	global_load_dwordx4 v[136:139], v30, s[6:7] nt
	global_load_dwordx4 v[140:143], v31, s[6:7] nt
	s_add_u32 s6, s6, 4096
	s_addc_u32 s7, s7, 0
	global_load_dwordx4 v[144:147], v30, s[6:7] nt
	global_load_dwordx4 v[148:151], v31, s[6:7] nt
	s_add_u32 s6, s6, 4096
	s_addc_u32 s7, s7, 0
	global_load_dwordx4 v[152:155], v30, s[6:7] nt
	global_load_dwordx4 v[156:159], v31, s[6:7] nt
	s_add_u32 s6, s6, 4096
	s_addc_u32 s7, s7, 0
	global_load_dwordx4 v[160:163], v30, s[6:7] nt
	global_load_dwordx4 v[164:167], v31, s[6:7] nt
	s_add_u32 s6, s6, 4160
	s_addc_u32 s7, s7, 0
	global_load_dwordx4 v[168:171], v30, s[6:7] nt
	global_load_dwordx4 v[172:175], v31, s[6:7] nt
	s_add_u32 s6, s6, 4096
	s_addc_u32 s7, s7, 0
	global_load_dwordx4 v[176:179], v30, s[6:7] nt
	global_load_dwordx4 v[180:183], v31, s[6:7] nt
	s_add_u32 s6, s6, 4096
	s_addc_u32 s7, s7, 0
	global_load_dwordx4 v[184:187], v30, s[6:7] nt
	global_load_dwordx4 v[188:191], v31, s[6:7] nt
	v_ashrrev_i32_e32 v16, 3, v224
	v_lshlrev_b32_e32 v9, 3, v224
	v_and_b32_e32 v9, 56, v9
	s_movk_i32 s8, 0x104
	v_mul_lo_u32 v10, v14, s8
	v_lshl_add_u32 v15, v20, 2, v10
	v_add_u32_e32 v17, 0x2080, v15
	v_mul_u32_u24_e32 v21, 0x104, v9
	v_lshl_add_u32 v19, v16, 2, v21
	v_add_u32_e32 v18, 0x400, v19
	v_lshlrev_b32_e32 v12, 11, v16
	v_lshl_add_u32 v12, v9, 1, v12
	s_lshr_b32 s8, s2, 4
	s_lshl_b32 s8, s8, 17
	s_lshl_b32 s9, s3, 1
	s_add_u32 s8, s8, s9
	s_add_u32 s8, s20, s8
	s_addc_u32 s9, s21, 0
	s_waitcnt vmcnt(14)
	ds_write2_b32 v15, v128, v129 offset1:1
	ds_write2_b32 v15, v130, v131 offset0:2 offset1:3
	ds_write2_b32 v17, v132, v133 offset1:1
	ds_write2_b32 v17, v134, v135 offset0:2 offset1:3
	s_waitcnt lgkmcnt(0)
	s_barrier
	ds_read2_b32 v[0:1], v19 offset1:65
	ds_read2_b32 v[2:3], v19 offset0:130 offset1:195
	ds_read2_b32 v[4:5], v18 offset0:4 offset1:69
	ds_read2_b32 v[6:7], v18 offset0:134 offset1:199
	s_waitcnt lgkmcnt(0)
	v_cvt_pk_bf16_f32 v22, v0, v1
	v_cvt_pk_bf16_f32 v23, v2, v3
	v_cvt_pk_bf16_f32 v24, v4, v5
	v_cvt_pk_bf16_f32 v25, v6, v7
	global_store_dwordx4 v12, v[22:25], s[8:9]
	s_waitcnt vmcnt(13)
	v_add_u32_e32 v26, 0x4200, v15
	v_add_u32_e32 v27, 0x4200, v17
	v_add_u32_e32 v28, 0x4200, v19
	v_add_u32_e32 v29, 0x4200, v18
	ds_write2_b32 v26, v136, v137 offset1:1
	ds_write2_b32 v26, v138, v139 offset0:2 offset1:3
	ds_write2_b32 v27, v140, v141 offset1:1
	ds_write2_b32 v27, v142, v143 offset0:2 offset1:3
	s_waitcnt lgkmcnt(0)
	s_barrier
	ds_read2_b32 v[0:1], v28 offset1:65
	ds_read2_b32 v[2:3], v28 offset0:130 offset1:195
	ds_read2_b32 v[4:5], v29 offset0:4 offset1:69
	ds_read2_b32 v[6:7], v29 offset0:134 offset1:199
	s_add_u32 s8, s8, 0x200000
	s_addc_u32 s9, s9, 0
	s_waitcnt lgkmcnt(0)
	v_cvt_pk_bf16_f32 v22, v0, v1
	v_cvt_pk_bf16_f32 v23, v2, v3
	v_cvt_pk_bf16_f32 v24, v4, v5
	v_cvt_pk_bf16_f32 v25, v6, v7
	global_store_dwordx4 v12, v[22:25], s[8:9]
	s_waitcnt vmcnt(12)
	ds_write2_b32 v15, v144, v145 offset1:1
	ds_write2_b32 v15, v146, v147 offset0:2 offset1:3
	ds_write2_b32 v17, v148, v149 offset1:1
	ds_write2_b32 v17, v150, v151 offset0:2 offset1:3
	s_waitcnt lgkmcnt(0)
	s_barrier
; __device__ __forceinline__ unsigned cvt_pk_bf16(float lo, float hi) { unsigned r; asm volatile("v_cvt_pk_bf16_f32 %0, %1, %2" : "=v"(r) : "v"(lo), "v"(hi)); return r; }
; __device__ void phase0(const Params& p, LAS unsigned char* lds) {
;     ...
;         for (; job < 2048; job += gridDim.x) {
;             const int kt = job & 15, ntile = job >> 4; const int n0 = ntile * 64, k0 = kt * 64;
;             T[r0 * 65 + c4] = va[0]; T[r0 * 65 + c4 + 1] = va[1]; T[r0 * 65 + c4 + 2] = va[2]; T[r0 * 65 + c4 + 3] = va[3];
;             T[(r0 + 32) * 65 + c4] = vb[0]; T[(r0 + 32) * 65 + c4 + 1] = vb[1]; T[(r0 + 32) * 65 + c4 + 2] = vb[2]; T[(r0 + 32) * 65 + c4 + 3] = vb[3];
;             __syncthreads();
;             const int nj = job + gridDim.x;
;             if (nj < 2048) { const int kt2 = nj & 15, nt2 = nj >> 4; const int n2 = nt2 * 64, k2 = kt2 * 64; const int c2 = n2 < 5120 ? n2 : n2 + 16;
;                 va = __builtin_nontemporal_load((const f32x4*)(p.in_w + (size_t)(k2 + r0) * 8208 + c2 + c4)); vb = __builtin_nontemporal_load((const f32x4*)(p.in_w + (size_t)(k2 + r0 + 32) * 8208 + c2 + c4)); }
;             { const int n = tid >> 3, kc = (tid & 7) * 8; float f[8];
; #pragma unroll
;               for (int j = 0; j < 8; ++j) f[j] = T[(kc + j) * 65 + n];
;               u32x4 w; w.x = cvt_pk_bf16(f[0], f[1]); w.y = cvt_pk_bf16(f[2], f[3]); w.z = cvt_pk_bf16(f[4], f[5]); w.w = cvt_pk_bf16(f[6], f[7]);
;               *(u32x4*)(WinT + (size_t)(n0 + n) * 1024 + k0 + kc) = w; }
;             __syncthreads();
;         }
	ds_read2_b32 v[0:1], v19 offset1:65
	ds_read2_b32 v[2:3], v19 offset0:130 offset1:195
	ds_read2_b32 v[4:5], v18 offset0:4 offset1:69
	ds_read2_b32 v[6:7], v18 offset0:134 offset1:199
	s_add_u32 s8, s8, 0x200000
	s_addc_u32 s9, s9, 0
	s_waitcnt lgkmcnt(0)
	v_cvt_pk_bf16_f32 v22, v0, v1
	v_cvt_pk_bf16_f32 v23, v2, v3
	v_cvt_pk_bf16_f32 v24, v4, v5
	v_cvt_pk_bf16_f32 v25, v6, v7
	global_store_dwordx4 v12, v[22:25], s[8:9]
	s_waitcnt vmcnt(11)
	ds_write2_b32 v26, v152, v153 offset1:1
	ds_write2_b32 v26, v154, v155 offset0:2 offset1:3
	ds_write2_b32 v27, v156, v157 offset1:1
	ds_write2_b32 v27, v158, v159 offset0:2 offset1:3
	s_waitcnt lgkmcnt(0)
	s_barrier
	ds_read2_b32 v[0:1], v28 offset1:65
	ds_read2_b32 v[2:3], v28 offset0:130 offset1:195
	ds_read2_b32 v[4:5], v29 offset0:4 offset1:69
	ds_read2_b32 v[6:7], v29 offset0:134 offset1:199
	s_add_u32 s8, s8, 0x200000
	s_addc_u32 s9, s9, 0
	s_waitcnt lgkmcnt(0)
	v_cvt_pk_bf16_f32 v22, v0, v1
	v_cvt_pk_bf16_f32 v23, v2, v3
	v_cvt_pk_bf16_f32 v24, v4, v5
	v_cvt_pk_bf16_f32 v25, v6, v7
	global_store_dwordx4 v12, v[22:25], s[8:9]
	s_waitcnt vmcnt(10)
	ds_write2_b32 v15, v160, v161 offset1:1
	ds_write2_b32 v15, v162, v163 offset0:2 offset1:3
	ds_write2_b32 v17, v164, v165 offset1:1
	ds_write2_b32 v17, v166, v167 offset0:2 offset1:3
	s_waitcnt lgkmcnt(0)
	s_barrier
	ds_read2_b32 v[0:1], v19 offset1:65
	ds_read2_b32 v[2:3], v19 offset0:130 offset1:195
	ds_read2_b32 v[4:5], v18 offset0:4 offset1:69
	ds_read2_b32 v[6:7], v18 offset0:134 offset1:199
	s_add_u32 s8, s8, 0x200000
	s_addc_u32 s9, s9, 0
	s_waitcnt lgkmcnt(0)
	v_cvt_pk_bf16_f32 v22, v0, v1
	v_cvt_pk_bf16_f32 v23, v2, v3
	v_cvt_pk_bf16_f32 v24, v4, v5
	v_cvt_pk_bf16_f32 v25, v6, v7
	global_store_dwordx4 v12, v[22:25], s[8:9]
	s_waitcnt vmcnt(9)
	ds_write2_b32 v26, v168, v169 offset1:1
	ds_write2_b32 v26, v170, v171 offset0:2 offset1:3
	ds_write2_b32 v27, v172, v173 offset1:1
	ds_write2_b32 v27, v174, v175 offset0:2 offset1:3
	s_waitcnt lgkmcnt(0)
	s_barrier
	ds_read2_b32 v[0:1], v28 offset1:65
	ds_read2_b32 v[2:3], v28 offset0:130 offset1:195
	ds_read2_b32 v[4:5], v29 offset0:4 offset1:69
	ds_read2_b32 v[6:7], v29 offset0:134 offset1:199
	s_add_u32 s8, s8, 0x200000
	s_addc_u32 s9, s9, 0
	s_waitcnt lgkmcnt(0)
	v_cvt_pk_bf16_f32 v22, v0, v1
	v_cvt_pk_bf16_f32 v23, v2, v3
	v_cvt_pk_bf16_f32 v24, v4, v5
	v_cvt_pk_bf16_f32 v25, v6, v7
	global_store_dwordx4 v12, v[22:25], s[8:9]
	s_waitcnt vmcnt(8)
	ds_write2_b32 v15, v176, v177 offset1:1
	ds_write2_b32 v15, v178, v179 offset0:2 offset1:3
	ds_write2_b32 v17, v180, v181 offset1:1
	ds_write2_b32 v17, v182, v183 offset0:2 offset1:3
	s_waitcnt lgkmcnt(0)
	s_barrier
	ds_read2_b32 v[0:1], v19 offset1:65
	ds_read2_b32 v[2:3], v19 offset0:130 offset1:195
	ds_read2_b32 v[4:5], v18 offset0:4 offset1:69
	ds_read2_b32 v[6:7], v18 offset0:134 offset1:199
	s_add_u32 s8, s8, 0x200000
	s_addc_u32 s9, s9, 0
	s_waitcnt lgkmcnt(0)
	v_cvt_pk_bf16_f32 v22, v0, v1
	v_cvt_pk_bf16_f32 v23, v2, v3
	v_cvt_pk_bf16_f32 v24, v4, v5
	v_cvt_pk_bf16_f32 v25, v6, v7
	global_store_dwordx4 v12, v[22:25], s[8:9]
	s_waitcnt vmcnt(7)
	ds_write2_b32 v26, v184, v185 offset1:1
	ds_write2_b32 v26, v186, v187 offset0:2 offset1:3
	ds_write2_b32 v27, v188, v189 offset1:1
	ds_write2_b32 v27, v190, v191 offset0:2 offset1:3
	s_waitcnt lgkmcnt(0)
	s_barrier
	ds_read2_b32 v[0:1], v28 offset1:65
	ds_read2_b32 v[2:3], v28 offset0:130 offset1:195
	ds_read2_b32 v[4:5], v29 offset0:4 offset1:69
	ds_read2_b32 v[6:7], v29 offset0:134 offset1:199
	s_add_u32 s8, s8, 0x200000
	s_addc_u32 s9, s9, 0
	s_waitcnt lgkmcnt(0)
	v_cvt_pk_bf16_f32 v22, v0, v1
	v_cvt_pk_bf16_f32 v23, v2, v3
	v_cvt_pk_bf16_f32 v24, v4, v5
	v_cvt_pk_bf16_f32 v25, v6, v7
	global_store_dwordx4 v12, v[22:25], s[8:9]
	s_barrier
